# EpiSwiglu widened dwordx2 stores on top of epires+zero1, with one s_nop in the epilogue to keep K-loop 8-byte phases at baseline
# speedup vs baseline: 1.0221x; 1.0048x over previous
; __device__ __forceinline__ float sigmoidf_(float x) { return __builtin_amdgcn_rcpf(1.f + __expf(-x)); }
; __device__ __forceinline__ u32x2 pack4(const f32x4& a) { u32x2 w; w.x = pk2(a[0], a[1]); w.y = pk2(a[2], a[3]); return w; }
; #define EPI_LOOP_ROWS for (int am_ = 0; am_ < 8; ++am_)
; __device__ __forceinline__ float ss_rstd(const float* ssrow) { const f32x4 a = *(const f32x4*)ssrow, b = *(const f32x4*)(ssrow + 4), c = *(const f32x4*)(ssrow + 8), d = *(const f32x4*)(ssrow + 12);
;     const float s = ((a[0] + a[1]) + (a[2] + a[3])) + ((b[0] + b[1]) + (b[2] + b[3])) + ((c[0] + c[1]) + (c[2] + c[3])) + ((d[0] + d[1]) + (d[2] + d[3])); return rsqrtf(s * (1.f / D) + 1e-6f); }
;     __device__ __forceinline__ void operator()(const f32x4 (&acc)[2][2][4][2], const pg8::Unit& u, int wr, int wc, int fr, int fq) const { asm volatile("" : "+v"(fr), "+v"(fq));
;     ...
;         EPI_LOOP_ROWS { EPI_AM const int row = u.pm * 256 + ai * 128 + wr * 64 + m * 16 + fr; const float rstd = ss_rstd(ss + (size_t)row * 16);
; #pragma unroll
;             for (int bj = 0; bj < 2; ++bj) { const int col0 = u.pn * 256 + bj * 128 + wc * 32 + 8 * fq; const f32x4 g = acc[ai][bj][m][0] * rstd, up = acc[ai][bj][m][1] * rstd; f32x4 o;
; #pragma unroll
;                 for (int j = 0; j < 4; ++j) o[j] = g[j] * sigmoidf_(g[j]) * up[j];
;                 *(u32x2*)(act + (size_t)row * FF + (col0 >> 1)) = pack4(o); } }
.LBB0_191:
	v_and_b32_e32 v184, 16, v166
	v_lshlrev_b32_e32 v185, 3, v184
	v_lshrrev_b32_e32 v184, 1, v184
	v_sub_u32_e32 v184, v185, v184
	v_mov_b32_e32 v185, 0
	s_nop 0
	v_mov_b32_e32 v139, v148
	v_mov_b32_e32 v142, v149
	s_lshl_b32 s33, s33, 8
	s_add_i32 s33, s33, s71
	v_add_u32_e32 v142, s33, v142
	v_ashrrev_i32_e32 v143, 31, v142
	v_lshlrev_b64 v[144:145], 6, v[142:143]
	v_lshl_add_u64 v[160:161], s[16:17], 0, v[144:145]
	global_load_dwordx4 v[144:147], v[160:161], off offset:48
	global_load_dwordx4 v[152:155], v[160:161], off offset:32
	global_load_dwordx4 v[156:159], v[160:161], off offset:16
	s_nop 0
	global_load_dwordx4 v[160:163], v[160:161], off
	s_lshl_b32 s33, s80, 8
	s_or_b32 s33, s33, s74
	v_lshl_add_u32 v139, v139, 3, s33
	s_waitcnt vmcnt(0)
	v_add_f32_e32 v152, v152, v153
	v_add_f32_e32 v154, v154, v155
	v_mov_b32_e32 v164, v161
	v_mov_b32_e32 v165, v162
	v_mov_b32_e32 v161, v163
	v_mov_b32_e32 v162, v157
	v_mov_b32_e32 v163, v158
	v_mov_b32_e32 v157, v159
	v_pk_add_f32 v[160:161], v[164:165], v[160:161]
	v_pk_add_f32 v[156:157], v[162:163], v[156:157]
	v_pk_add_f32 v[160:161], v[160:161], v[160:161] op_sel:[0,1] op_sel_hi:[1,0]
	v_pk_add_f32 v[156:157], v[156:157], v[156:157] op_sel:[0,1] op_sel_hi:[1,0]
	v_mov_b32_e32 v161, v144
	v_mov_b32_e32 v157, v145
	v_mov_b32_e32 v153, v146
	v_mov_b32_e32 v155, v147
	v_pk_add_f32 v[144:145], v[160:161], v[156:157]
	v_pk_add_f32 v[146:147], v[152:153], v[154:155]
	s_nop 0
	v_pk_add_f32 v[144:145], v[144:145], v[146:147]
	s_nop 0
	v_add_f32_e32 v143, v144, v145
	v_fmamk_f32 v143, v143, 0x3a800000, v138
	v_cmp_gt_f32_e32 vcc, s64, v143
	v_mul_f32_e32 v144, 0x4b800000, v143
	s_nop 0
	v_cndmask_b32_e32 v143, v143, v144, vcc
	v_rsq_f32_e32 v143, v143
	s_nop 0
	v_mul_f32_e32 v144, 0x45800000, v143
	v_cndmask_b32_e32 v144, v143, v144, vcc
	v_pk_mul_f32 v[124:125], v[124:125], v[144:145] op_sel_hi:[1,0]
	v_pk_mul_f32 v[120:121], v[120:121], v[144:145] op_sel_hi:[1,0]
	v_mul_f32_e32 v143, 0xbfb8aa3b, v124
	v_exp_f32_e32 v143, v143
	v_pk_mul_f32 v[122:123], v[122:123], v[144:145] op_sel_hi:[1,0]
	v_pk_mul_f32 v[116:117], v[116:117], v[144:145] op_sel_hi:[1,0]
	v_pk_mul_f32 v[112:113], v[112:113], v[144:145] op_sel_hi:[1,0]
	v_add_f32_e32 v143, 1.0, v143
	v_rcp_f32_e32 v146, v143
	v_mul_f32_e32 v143, 0xbfb8aa3b, v125
	v_exp_f32_e32 v143, v143
	v_pk_mul_f32 v[114:115], v[114:115], v[144:145] op_sel_hi:[1,0]
	v_add_f32_e32 v143, 1.0, v143
	v_rcp_f32_e32 v147, v143
	s_nop 0
	v_pk_mul_f32 v[124:125], v[124:125], v[146:147]
	s_nop 0
	v_pk_mul_f32 v[120:121], v[120:121], v[124:125]
	v_pk_mul_f32 v[124:125], v[126:127], v[144:145] op_sel_hi:[1,0]
	v_cvt_pk_bf16_f32 v120, v120, v121
	v_mul_f32_e32 v126, 0xbfb8aa3b, v124
	v_mul_f32_e32 v127, 0xbfb8aa3b, v125
	v_exp_f32_e32 v126, v126
	v_exp_f32_e32 v127, v127
	v_add_f32_e32 v126, 1.0, v126
	v_add_f32_e32 v127, 1.0, v127
	v_rcp_f32_e32 v126, v126
	v_rcp_f32_e32 v127, v127
	s_nop 0
	v_pk_mul_f32 v[124:125], v[124:125], v[126:127]
	v_ashrrev_i32_e32 v126, 1, v139
	v_pk_mul_f32 v[122:123], v[122:123], v[124:125]
	v_mov_b64_e32 v[124:125], s[88:89]
	v_ashrrev_i32_e32 v127, 31, v126
	v_cvt_pk_bf16_f32 v121, v122, v123
	v_mad_i64_i32 v[122:123], s[38:39], v142, s59, v[124:125]
	v_lshlrev_b64 v[126:127], 1, v[126:127]
	v_lshl_add_u64 v[146:147], v[122:123], 0, v[126:127]
	v_mov_b32_e32 v172, v120
	v_mov_b32_e32 v173, v121
	v_lshl_add_u64 v[176:177], v[184:185], 0, v[146:147]
	v_mul_f32_e32 v120, 0xbfb8aa3b, v116
	v_mul_f32_e32 v121, 0xbfb8aa3b, v117
	v_exp_f32_e32 v120, v120
	v_exp_f32_e32 v121, v121
	v_add_u32_e32 v146, 16, v142
	v_ashrrev_i32_e32 v147, 31, v146
	v_add_f32_e32 v120, 1.0, v120
	v_add_f32_e32 v121, 1.0, v121
	v_rcp_f32_e32 v120, v120
	v_rcp_f32_e32 v121, v121
	s_nop 0
	v_pk_mul_f32 v[116:117], v[116:117], v[120:121]
	s_nop 0
	v_pk_mul_f32 v[112:113], v[112:113], v[116:117]
	v_pk_mul_f32 v[116:117], v[118:119], v[144:145] op_sel_hi:[1,0]
	v_cvt_pk_bf16_f32 v112, v112, v113
	v_mul_f32_e32 v118, 0xbfb8aa3b, v116
	v_mul_f32_e32 v119, 0xbfb8aa3b, v117
	v_exp_f32_e32 v118, v118
	v_exp_f32_e32 v119, v119
	v_add_f32_e32 v118, 1.0, v118
	v_add_f32_e32 v119, 1.0, v119
	v_rcp_f32_e32 v118, v118
	v_rcp_f32_e32 v119, v119
	s_nop 0
	v_pk_mul_f32 v[116:117], v[116:117], v[118:119]
	s_nop 0
	v_pk_mul_f32 v[114:115], v[114:115], v[116:117]
	v_add_u32_e32 v116, 0x80, v139
	v_cvt_pk_bf16_f32 v113, v114, v115
	v_ashrrev_i32_e32 v114, 1, v116
	v_ashrrev_i32_e32 v115, 31, v114
	v_lshlrev_b64 v[144:145], 1, v[114:115]
	v_lshl_add_u64 v[114:115], v[122:123], 0, v[144:145]
	v_mov_b32_e32 v174, v112
	v_mov_b32_e32 v175, v113
	s_nop 1
	v_permlane16_swap_b32 v172, v174
	v_permlane16_swap_b32 v173, v175
	global_store_dwordx4 v[176:177], v[172:175], off
	v_lshlrev_b64 v[112:113], 6, v[146:147]
	v_lshl_add_u64 v[152:153], s[16:17], 0, v[112:113]
	global_load_dwordx4 v[112:115], v[152:153], off offset:48
	global_load_dwordx4 v[116:119], v[152:153], off offset:32
	global_load_dwordx4 v[120:123], v[152:153], off offset:16
	s_nop 0
	global_load_dwordx4 v[152:155], v[152:153], off
	s_waitcnt vmcnt(0)
; __device__ __forceinline__ float sigmoidf_(float x) { return __builtin_amdgcn_rcpf(1.f + __expf(-x)); }
; __device__ __forceinline__ u32x2 pack4(const f32x4& a) { u32x2 w; w.x = pk2(a[0], a[1]); w.y = pk2(a[2], a[3]); return w; }
; #define EPI_LOOP_ROWS for (int am_ = 0; am_ < 8; ++am_)
; __device__ __forceinline__ float ss_rstd(const float* ssrow) { const f32x4 a = *(const f32x4*)ssrow, b = *(const f32x4*)(ssrow + 4), c = *(const f32x4*)(ssrow + 8), d = *(const f32x4*)(ssrow + 12);
;     const float s = ((a[0] + a[1]) + (a[2] + a[3])) + ((b[0] + b[1]) + (b[2] + b[3])) + ((c[0] + c[1]) + (c[2] + c[3])) + ((d[0] + d[1]) + (d[2] + d[3])); return rsqrtf(s * (1.f / D) + 1e-6f); }
;     __device__ __forceinline__ void operator()(const f32x4 (&acc)[2][2][4][2], const pg8::Unit& u, int wr, int wc, int fr, int fq) const { asm volatile("" : "+v"(fr), "+v"(fq));
;     ...
;         EPI_LOOP_ROWS { EPI_AM const int row = u.pm * 256 + ai * 128 + wr * 64 + m * 16 + fr; const float rstd = ss_rstd(ss + (size_t)row * 16);
; #pragma unroll
;             for (int bj = 0; bj < 2; ++bj) { const int col0 = u.pn * 256 + bj * 128 + wc * 32 + 8 * fq; const f32x4 g = acc[ai][bj][m][0] * rstd, up = acc[ai][bj][m][1] * rstd; f32x4 o;
; #pragma unroll
;                 for (int j = 0; j < 4; ++j) o[j] = g[j] * sigmoidf_(g[j]) * up[j];
;                 *(u32x2*)(act + (size_t)row * FF + (col0 >> 1)) = pack4(o); } }
	v_add_f32_e32 v116, v116, v117
	v_add_f32_e32 v118, v118, v119
	v_mov_b32_e32 v156, v153
	v_mov_b32_e32 v157, v154
	v_mov_b32_e32 v153, v155
	v_mov_b32_e32 v154, v121
	v_mov_b32_e32 v155, v122
	v_mov_b32_e32 v121, v123
	v_pk_add_f32 v[152:153], v[156:157], v[152:153]
	v_pk_add_f32 v[120:121], v[154:155], v[120:121]
	v_pk_add_f32 v[152:153], v[152:153], v[152:153] op_sel:[0,1] op_sel_hi:[1,0]
	v_pk_add_f32 v[120:121], v[120:121], v[120:121] op_sel:[0,1] op_sel_hi:[1,0]
	v_mov_b32_e32 v153, v112
	v_mov_b32_e32 v121, v113
	v_mov_b32_e32 v117, v114
	v_mov_b32_e32 v119, v115
	v_pk_add_f32 v[112:113], v[152:153], v[120:121]
	v_pk_add_f32 v[114:115], v[116:117], v[118:119]
	s_nop 0
	v_pk_add_f32 v[112:113], v[112:113], v[114:115]
	s_nop 0
	v_add_f32_e32 v112, v112, v113
	v_fmamk_f32 v112, v112, 0x3a800000, v138
	v_cmp_gt_f32_e32 vcc, s64, v112
	v_mul_f32_e32 v113, 0x4b800000, v112
	s_nop 0
	v_cndmask_b32_e32 v112, v112, v113, vcc
	v_rsq_f32_e32 v112, v112
	s_nop 0
	v_mul_f32_e32 v113, 0x45800000, v112
	v_cndmask_b32_e32 v112, v112, v113, vcc
	v_pk_mul_f32 v[108:109], v[108:109], v[112:113] op_sel_hi:[1,0]
	s_nop 0
	v_mul_f32_e32 v113, 0xbfb8aa3b, v108
	v_exp_f32_e32 v113, v113
	s_nop 0
	v_add_f32_e32 v113, 1.0, v113
	v_rcp_f32_e32 v114, v113
	v_mul_f32_e32 v113, 0xbfb8aa3b, v109
	v_exp_f32_e32 v113, v113
	s_nop 0
	v_add_f32_e32 v113, 1.0, v113
	v_rcp_f32_e32 v115, v113
	v_pk_mul_f32 v[104:105], v[104:105], v[112:113] op_sel_hi:[1,0]
	v_pk_mul_f32 v[106:107], v[106:107], v[112:113] op_sel_hi:[1,0]
	v_pk_mul_f32 v[100:101], v[100:101], v[112:113] op_sel_hi:[1,0]
	v_pk_mul_f32 v[108:109], v[108:109], v[114:115]
	v_pk_mul_f32 v[96:97], v[96:97], v[112:113] op_sel_hi:[1,0]
	v_pk_mul_f32 v[104:105], v[104:105], v[108:109]
	v_pk_mul_f32 v[108:109], v[110:111], v[112:113] op_sel_hi:[1,0]
	v_cvt_pk_bf16_f32 v104, v104, v105
	v_mul_f32_e32 v110, 0xbfb8aa3b, v108
	v_mul_f32_e32 v111, 0xbfb8aa3b, v109
	v_exp_f32_e32 v110, v110
	v_exp_f32_e32 v111, v111
	v_pk_mul_f32 v[98:99], v[98:99], v[112:113] op_sel_hi:[1,0]
	v_add_f32_e32 v110, 1.0, v110
	v_add_f32_e32 v111, 1.0, v111
	v_rcp_f32_e32 v110, v110
	v_rcp_f32_e32 v111, v111
	s_nop 0
	v_pk_mul_f32 v[108:109], v[108:109], v[110:111]
	s_nop 0
	v_pk_mul_f32 v[106:107], v[106:107], v[108:109]
	s_nop 0
	v_cvt_pk_bf16_f32 v105, v106, v107
	v_mad_i64_i32 v[106:107], s[38:39], v146, s59, v[124:125]
	v_lshl_add_u64 v[108:109], v[106:107], 0, v[126:127]
	v_mov_b32_e32 v180, v104
	v_mov_b32_e32 v181, v105
	v_lshl_add_u64 v[178:179], v[184:185], 0, v[108:109]
	v_mul_f32_e32 v104, 0xbfb8aa3b, v100
	v_mul_f32_e32 v105, 0xbfb8aa3b, v101
	v_exp_f32_e32 v104, v104
	v_exp_f32_e32 v105, v105
	v_add_u32_e32 v108, 32, v142
	v_ashrrev_i32_e32 v109, 31, v108
	v_add_f32_e32 v104, 1.0, v104
	v_add_f32_e32 v105, 1.0, v105
	v_rcp_f32_e32 v104, v104
	v_rcp_f32_e32 v105, v105
	s_nop 0
	v_pk_mul_f32 v[100:101], v[100:101], v[104:105]
	s_nop 0
	v_pk_mul_f32 v[96:97], v[96:97], v[100:101]
	v_pk_mul_f32 v[100:101], v[102:103], v[112:113] op_sel_hi:[1,0]
	v_cvt_pk_bf16_f32 v96, v96, v97
	v_mul_f32_e32 v102, 0xbfb8aa3b, v100
	v_mul_f32_e32 v103, 0xbfb8aa3b, v101
	v_exp_f32_e32 v102, v102
	v_exp_f32_e32 v103, v103
	v_add_f32_e32 v102, 1.0, v102
	v_add_f32_e32 v103, 1.0, v103
	v_rcp_f32_e32 v102, v102
	v_rcp_f32_e32 v103, v103
	s_nop 0
	v_pk_mul_f32 v[100:101], v[100:101], v[102:103]
	s_nop 0
	v_pk_mul_f32 v[98:99], v[98:99], v[100:101]
	s_nop 0
	v_cvt_pk_bf16_f32 v97, v98, v99
	v_lshl_add_u64 v[98:99], v[106:107], 0, v[144:145]
	v_mov_b32_e32 v182, v96
	v_mov_b32_e32 v183, v97
	s_nop 1
	v_permlane16_swap_b32 v180, v182
	v_permlane16_swap_b32 v181, v183
	global_store_dwordx4 v[178:179], v[180:183], off
	v_lshlrev_b64 v[96:97], 6, v[108:109]
	v_lshl_add_u64 v[110:111], s[16:17], 0, v[96:97]
	global_load_dwordx4 v[96:99], v[110:111], off offset:48
	global_load_dwordx4 v[100:103], v[110:111], off offset:32
	global_load_dwordx4 v[104:107], v[110:111], off offset:16
	s_nop 0
	global_load_dwordx4 v[110:113], v[110:111], off
	s_waitcnt vmcnt(0)
	v_add_f32_e32 v100, v100, v101
	v_add_f32_e32 v102, v102, v103
	v_mov_b32_e32 v114, v111
	v_mov_b32_e32 v115, v112
	v_mov_b32_e32 v111, v113
	v_mov_b32_e32 v112, v105
	v_mov_b32_e32 v113, v106
	v_mov_b32_e32 v105, v107
	v_pk_add_f32 v[110:111], v[114:115], v[110:111]
	v_pk_add_f32 v[104:105], v[112:113], v[104:105]
	v_pk_add_f32 v[110:111], v[110:111], v[110:111] op_sel:[0,1] op_sel_hi:[1,0]
	v_pk_add_f32 v[104:105], v[104:105], v[104:105] op_sel:[0,1] op_sel_hi:[1,0]
	v_mov_b32_e32 v111, v96
	v_mov_b32_e32 v105, v97
	v_mov_b32_e32 v101, v98
	v_mov_b32_e32 v103, v99
	v_pk_add_f32 v[96:97], v[110:111], v[104:105]
	v_pk_add_f32 v[98:99], v[100:101], v[102:103]
	s_nop 0
	v_pk_add_f32 v[96:97], v[96:97], v[98:99]
	s_nop 0
	v_add_f32_e32 v96, v96, v97
	v_fmamk_f32 v96, v96, 0x3a800000, v138
	v_cmp_gt_f32_e32 vcc, s64, v96
	v_mul_f32_e32 v97, 0x4b800000, v96
	s_nop 0
	v_cndmask_b32_e32 v96, v96, v97, vcc
	v_rsq_f32_e32 v96, v96
	s_nop 0
	v_mul_f32_e32 v97, 0x45800000, v96
	v_cndmask_b32_e32 v96, v96, v97, vcc
	v_pk_mul_f32 v[92:93], v[92:93], v[96:97] op_sel_hi:[1,0]
	s_nop 0
	v_mul_f32_e32 v97, 0xbfb8aa3b, v92
	v_exp_f32_e32 v97, v97
	s_nop 0
	v_add_f32_e32 v97, 1.0, v97
	v_rcp_f32_e32 v98, v97
	v_mul_f32_e32 v97, 0xbfb8aa3b, v93
	v_exp_f32_e32 v97, v97
	s_nop 0
	v_add_f32_e32 v97, 1.0, v97
	v_rcp_f32_e32 v99, v97
	v_pk_mul_f32 v[88:89], v[88:89], v[96:97] op_sel_hi:[1,0]
	v_pk_mul_f32 v[90:91], v[90:91], v[96:97] op_sel_hi:[1,0]
	v_pk_mul_f32 v[84:85], v[84:85], v[96:97] op_sel_hi:[1,0]
	v_pk_mul_f32 v[92:93], v[92:93], v[98:99]
	v_pk_mul_f32 v[80:81], v[80:81], v[96:97] op_sel_hi:[1,0]
	v_pk_mul_f32 v[88:89], v[88:89], v[92:93]
; __device__ __forceinline__ float sigmoidf_(float x) { return __builtin_amdgcn_rcpf(1.f + __expf(-x)); }
; __device__ __forceinline__ u32x2 pack4(const f32x4& a) { u32x2 w; w.x = pk2(a[0], a[1]); w.y = pk2(a[2], a[3]); return w; }
; #define EPI_LOOP_ROWS for (int am_ = 0; am_ < 8; ++am_)
; __device__ __forceinline__ float ss_rstd(const float* ssrow) { const f32x4 a = *(const f32x4*)ssrow, b = *(const f32x4*)(ssrow + 4), c = *(const f32x4*)(ssrow + 8), d = *(const f32x4*)(ssrow + 12);
;     const float s = ((a[0] + a[1]) + (a[2] + a[3])) + ((b[0] + b[1]) + (b[2] + b[3])) + ((c[0] + c[1]) + (c[2] + c[3])) + ((d[0] + d[1]) + (d[2] + d[3])); return rsqrtf(s * (1.f / D) + 1e-6f); }
;     __device__ __forceinline__ void operator()(const f32x4 (&acc)[2][2][4][2], const pg8::Unit& u, int wr, int wc, int fr, int fq) const { asm volatile("" : "+v"(fr), "+v"(fq));
;     ...
;         EPI_LOOP_ROWS { EPI_AM const int row = u.pm * 256 + ai * 128 + wr * 64 + m * 16 + fr; const float rstd = ss_rstd(ss + (size_t)row * 16);
; #pragma unroll
;             for (int bj = 0; bj < 2; ++bj) { const int col0 = u.pn * 256 + bj * 128 + wc * 32 + 8 * fq; const f32x4 g = acc[ai][bj][m][0] * rstd, up = acc[ai][bj][m][1] * rstd; f32x4 o;
; #pragma unroll
;                 for (int j = 0; j < 4; ++j) o[j] = g[j] * sigmoidf_(g[j]) * up[j];
;                 *(u32x2*)(act + (size_t)row * FF + (col0 >> 1)) = pack4(o); } }
	v_pk_mul_f32 v[92:93], v[94:95], v[96:97] op_sel_hi:[1,0]
	v_cvt_pk_bf16_f32 v88, v88, v89
	v_mul_f32_e32 v94, 0xbfb8aa3b, v92
	v_mul_f32_e32 v95, 0xbfb8aa3b, v93
	v_exp_f32_e32 v94, v94
	v_exp_f32_e32 v95, v95
	v_pk_mul_f32 v[82:83], v[82:83], v[96:97] op_sel_hi:[1,0]
	v_add_f32_e32 v94, 1.0, v94
	v_add_f32_e32 v95, 1.0, v95
	v_rcp_f32_e32 v94, v94
	v_rcp_f32_e32 v95, v95
	s_nop 0
	v_pk_mul_f32 v[92:93], v[92:93], v[94:95]
	s_nop 0
	v_pk_mul_f32 v[90:91], v[90:91], v[92:93]
	s_nop 0
	v_cvt_pk_bf16_f32 v89, v90, v91
	v_mad_i64_i32 v[90:91], s[38:39], v108, s59, v[124:125]
	v_lshl_add_u64 v[92:93], v[90:91], 0, v[126:127]
	v_mov_b32_e32 v172, v88
	v_mov_b32_e32 v173, v89
	v_lshl_add_u64 v[176:177], v[184:185], 0, v[92:93]
	v_mul_f32_e32 v88, 0xbfb8aa3b, v84
	v_mul_f32_e32 v89, 0xbfb8aa3b, v85
	v_exp_f32_e32 v88, v88
	v_exp_f32_e32 v89, v89
	v_add_u32_e32 v92, 48, v142
	v_ashrrev_i32_e32 v93, 31, v92
	v_add_f32_e32 v88, 1.0, v88
	v_add_f32_e32 v89, 1.0, v89
	v_rcp_f32_e32 v88, v88
	v_rcp_f32_e32 v89, v89
	s_nop 0
	v_pk_mul_f32 v[84:85], v[84:85], v[88:89]
	s_nop 0
	v_pk_mul_f32 v[80:81], v[80:81], v[84:85]
	v_pk_mul_f32 v[84:85], v[86:87], v[96:97] op_sel_hi:[1,0]
	v_cvt_pk_bf16_f32 v80, v80, v81
	v_mul_f32_e32 v86, 0xbfb8aa3b, v84
	v_mul_f32_e32 v87, 0xbfb8aa3b, v85
	v_exp_f32_e32 v86, v86
	v_exp_f32_e32 v87, v87
	v_add_f32_e32 v86, 1.0, v86
	v_add_f32_e32 v87, 1.0, v87
	v_rcp_f32_e32 v86, v86
	v_rcp_f32_e32 v87, v87
	s_nop 0
	v_pk_mul_f32 v[84:85], v[84:85], v[86:87]
	s_nop 0
	v_pk_mul_f32 v[82:83], v[82:83], v[84:85]
	s_nop 0
	v_cvt_pk_bf16_f32 v81, v82, v83
	v_lshl_add_u64 v[82:83], v[90:91], 0, v[144:145]
	v_mov_b32_e32 v174, v80
	v_mov_b32_e32 v175, v81
	s_nop 1
	v_permlane16_swap_b32 v172, v174
	v_permlane16_swap_b32 v173, v175
	global_store_dwordx4 v[176:177], v[172:175], off
	v_lshlrev_b64 v[80:81], 6, v[92:93]
	v_lshl_add_u64 v[94:95], s[16:17], 0, v[80:81]
	global_load_dwordx4 v[80:83], v[94:95], off offset:48
	global_load_dwordx4 v[84:87], v[94:95], off offset:32
	global_load_dwordx4 v[88:91], v[94:95], off offset:16
	s_nop 0
	global_load_dwordx4 v[94:97], v[94:95], off
	s_waitcnt vmcnt(0)
	v_add_f32_e32 v84, v84, v85
	v_add_f32_e32 v86, v86, v87
	v_mov_b32_e32 v98, v95
	v_mov_b32_e32 v99, v96
	v_mov_b32_e32 v95, v97
	v_mov_b32_e32 v96, v89
	v_mov_b32_e32 v97, v90
	v_mov_b32_e32 v89, v91
	v_pk_add_f32 v[94:95], v[98:99], v[94:95]
	v_pk_add_f32 v[88:89], v[96:97], v[88:89]
	v_pk_add_f32 v[94:95], v[94:95], v[94:95] op_sel:[0,1] op_sel_hi:[1,0]
	v_pk_add_f32 v[88:89], v[88:89], v[88:89] op_sel:[0,1] op_sel_hi:[1,0]
	v_mov_b32_e32 v95, v80
	v_mov_b32_e32 v89, v81
	v_mov_b32_e32 v85, v82
	v_mov_b32_e32 v87, v83
	v_pk_add_f32 v[80:81], v[94:95], v[88:89]
	v_pk_add_f32 v[82:83], v[84:85], v[86:87]
	s_nop 0
	v_pk_add_f32 v[80:81], v[80:81], v[82:83]
	s_nop 0
	v_add_f32_e32 v80, v80, v81
	v_fmamk_f32 v80, v80, 0x3a800000, v138
	v_cmp_gt_f32_e32 vcc, s64, v80
	v_mul_f32_e32 v81, 0x4b800000, v80
	s_nop 0
	v_cndmask_b32_e32 v80, v80, v81, vcc
	v_rsq_f32_e32 v80, v80
	s_nop 0
	v_mul_f32_e32 v81, 0x45800000, v80
	v_cndmask_b32_e32 v80, v80, v81, vcc
	v_pk_mul_f32 v[76:77], v[76:77], v[80:81] op_sel_hi:[1,0]
	s_nop 0
	v_mul_f32_e32 v81, 0xbfb8aa3b, v76
	v_exp_f32_e32 v81, v81
	s_nop 0
	v_add_f32_e32 v81, 1.0, v81
	v_rcp_f32_e32 v82, v81
	v_mul_f32_e32 v81, 0xbfb8aa3b, v77
	v_exp_f32_e32 v81, v81
	s_nop 0
	v_add_f32_e32 v81, 1.0, v81
	v_rcp_f32_e32 v83, v81
	v_pk_mul_f32 v[72:73], v[72:73], v[80:81] op_sel_hi:[1,0]
	v_pk_mul_f32 v[74:75], v[74:75], v[80:81] op_sel_hi:[1,0]
	v_pk_mul_f32 v[68:69], v[68:69], v[80:81] op_sel_hi:[1,0]
	v_pk_mul_f32 v[76:77], v[76:77], v[82:83]
	v_pk_mul_f32 v[64:65], v[64:65], v[80:81] op_sel_hi:[1,0]
	v_pk_mul_f32 v[72:73], v[72:73], v[76:77]
	v_pk_mul_f32 v[76:77], v[78:79], v[80:81] op_sel_hi:[1,0]
	v_cvt_pk_bf16_f32 v72, v72, v73
	v_mul_f32_e32 v78, 0xbfb8aa3b, v76
	v_mul_f32_e32 v79, 0xbfb8aa3b, v77
	v_exp_f32_e32 v78, v78
	v_exp_f32_e32 v79, v79
	v_pk_mul_f32 v[66:67], v[66:67], v[80:81] op_sel_hi:[1,0]
	v_add_f32_e32 v78, 1.0, v78
	v_add_f32_e32 v79, 1.0, v79
	v_rcp_f32_e32 v78, v78
	v_rcp_f32_e32 v79, v79
	s_nop 0
	v_pk_mul_f32 v[76:77], v[76:77], v[78:79]
	s_nop 0
	v_pk_mul_f32 v[74:75], v[74:75], v[76:77]
	s_nop 0
	v_cvt_pk_bf16_f32 v73, v74, v75
	v_mad_i64_i32 v[74:75], s[38:39], v92, s59, v[124:125]
	v_lshl_add_u64 v[76:77], v[74:75], 0, v[126:127]
	v_mov_b32_e32 v180, v72
	v_mov_b32_e32 v181, v73
	v_lshl_add_u64 v[178:179], v[184:185], 0, v[76:77]
	v_mul_f32_e32 v72, 0xbfb8aa3b, v68
	v_mul_f32_e32 v73, 0xbfb8aa3b, v69
	v_exp_f32_e32 v72, v72
	v_exp_f32_e32 v73, v73
	v_add_u32_e32 v76, 0x80, v142
	v_ashrrev_i32_e32 v77, 31, v76
	v_add_f32_e32 v72, 1.0, v72
	v_add_f32_e32 v73, 1.0, v73
	v_rcp_f32_e32 v72, v72
	v_rcp_f32_e32 v73, v73
	s_nop 0
	v_pk_mul_f32 v[68:69], v[68:69], v[72:73]
	s_nop 0
	v_pk_mul_f32 v[64:65], v[64:65], v[68:69]
	v_pk_mul_f32 v[68:69], v[70:71], v[80:81] op_sel_hi:[1,0]
	v_cvt_pk_bf16_f32 v64, v64, v65
	v_mul_f32_e32 v70, 0xbfb8aa3b, v68
	v_mul_f32_e32 v71, 0xbfb8aa3b, v69
	v_exp_f32_e32 v70, v70
	v_exp_f32_e32 v71, v71
	v_add_f32_e32 v70, 1.0, v70
	v_add_f32_e32 v71, 1.0, v71
	v_rcp_f32_e32 v70, v70
	v_rcp_f32_e32 v71, v71
	s_nop 0
	v_pk_mul_f32 v[68:69], v[68:69], v[70:71]
	s_nop 0
	v_pk_mul_f32 v[66:67], v[66:67], v[68:69]
	s_nop 0
	v_cvt_pk_bf16_f32 v65, v66, v67
	v_lshl_add_u64 v[66:67], v[74:75], 0, v[144:145]
	v_mov_b32_e32 v182, v64
	v_mov_b32_e32 v183, v65
	s_nop 1
	v_permlane16_swap_b32 v180, v182
	v_permlane16_swap_b32 v181, v183
	global_store_dwordx4 v[178:179], v[180:183], off
	v_lshlrev_b64 v[64:65], 6, v[76:77]
	v_lshl_add_u64 v[78:79], s[16:17], 0, v[64:65]
	global_load_dwordx4 v[64:67], v[78:79], off offset:48
	global_load_dwordx4 v[68:71], v[78:79], off offset:32
	global_load_dwordx4 v[72:75], v[78:79], off offset:16
	s_nop 0
	global_load_dwordx4 v[78:81], v[78:79], off
	s_waitcnt vmcnt(0)
; __device__ __forceinline__ float sigmoidf_(float x) { return __builtin_amdgcn_rcpf(1.f + __expf(-x)); }
; __device__ __forceinline__ u32x2 pack4(const f32x4& a) { u32x2 w; w.x = pk2(a[0], a[1]); w.y = pk2(a[2], a[3]); return w; }
; #define EPI_LOOP_ROWS for (int am_ = 0; am_ < 8; ++am_)
; __device__ __forceinline__ float ss_rstd(const float* ssrow) { const f32x4 a = *(const f32x4*)ssrow, b = *(const f32x4*)(ssrow + 4), c = *(const f32x4*)(ssrow + 8), d = *(const f32x4*)(ssrow + 12);
;     const float s = ((a[0] + a[1]) + (a[2] + a[3])) + ((b[0] + b[1]) + (b[2] + b[3])) + ((c[0] + c[1]) + (c[2] + c[3])) + ((d[0] + d[1]) + (d[2] + d[3])); return rsqrtf(s * (1.f / D) + 1e-6f); }
;     __device__ __forceinline__ void operator()(const f32x4 (&acc)[2][2][4][2], const pg8::Unit& u, int wr, int wc, int fr, int fq) const { asm volatile("" : "+v"(fr), "+v"(fq));
;     ...
;         EPI_LOOP_ROWS { EPI_AM const int row = u.pm * 256 + ai * 128 + wr * 64 + m * 16 + fr; const float rstd = ss_rstd(ss + (size_t)row * 16);
; #pragma unroll
;             for (int bj = 0; bj < 2; ++bj) { const int col0 = u.pn * 256 + bj * 128 + wc * 32 + 8 * fq; const f32x4 g = acc[ai][bj][m][0] * rstd, up = acc[ai][bj][m][1] * rstd; f32x4 o;
; #pragma unroll
;                 for (int j = 0; j < 4; ++j) o[j] = g[j] * sigmoidf_(g[j]) * up[j];
;                 *(u32x2*)(act + (size_t)row * FF + (col0 >> 1)) = pack4(o); } }
	v_add_f32_e32 v68, v68, v69
	v_add_f32_e32 v70, v70, v71
	v_mov_b32_e32 v82, v79
	v_mov_b32_e32 v83, v80
	v_mov_b32_e32 v79, v81
	v_mov_b32_e32 v80, v73
	v_mov_b32_e32 v81, v74
	v_mov_b32_e32 v73, v75
	v_pk_add_f32 v[78:79], v[82:83], v[78:79]
	v_pk_add_f32 v[72:73], v[80:81], v[72:73]
	v_pk_add_f32 v[78:79], v[78:79], v[78:79] op_sel:[0,1] op_sel_hi:[1,0]
	v_pk_add_f32 v[72:73], v[72:73], v[72:73] op_sel:[0,1] op_sel_hi:[1,0]
	v_mov_b32_e32 v79, v64
	v_mov_b32_e32 v73, v65
	v_mov_b32_e32 v69, v66
	v_mov_b32_e32 v71, v67
	v_pk_add_f32 v[64:65], v[78:79], v[72:73]
	v_pk_add_f32 v[66:67], v[68:69], v[70:71]
	s_nop 0
	v_pk_add_f32 v[64:65], v[64:65], v[66:67]
	s_nop 0
	v_add_f32_e32 v64, v64, v65
	v_fmamk_f32 v64, v64, 0x3a800000, v138
	v_cmp_gt_f32_e32 vcc, s64, v64
	v_mul_f32_e32 v65, 0x4b800000, v64
	s_nop 0
	v_cndmask_b32_e32 v64, v64, v65, vcc
	v_rsq_f32_e32 v64, v64
	s_nop 0
	v_mul_f32_e32 v65, 0x45800000, v64
	v_cndmask_b32_e32 v64, v64, v65, vcc
	v_pk_mul_f32 v[60:61], v[60:61], v[64:65] op_sel_hi:[1,0]
	s_nop 0
	v_mul_f32_e32 v65, 0xbfb8aa3b, v60
	v_exp_f32_e32 v65, v65
	s_nop 0
	v_add_f32_e32 v65, 1.0, v65
	v_rcp_f32_e32 v66, v65
	v_mul_f32_e32 v65, 0xbfb8aa3b, v61
	v_exp_f32_e32 v65, v65
	s_nop 0
	v_add_f32_e32 v65, 1.0, v65
	v_rcp_f32_e32 v67, v65
	v_pk_mul_f32 v[56:57], v[56:57], v[64:65] op_sel_hi:[1,0]
	v_pk_mul_f32 v[58:59], v[58:59], v[64:65] op_sel_hi:[1,0]
	v_pk_mul_f32 v[52:53], v[52:53], v[64:65] op_sel_hi:[1,0]
	v_pk_mul_f32 v[60:61], v[60:61], v[66:67]
	v_pk_mul_f32 v[48:49], v[48:49], v[64:65] op_sel_hi:[1,0]
	v_pk_mul_f32 v[56:57], v[56:57], v[60:61]
	v_pk_mul_f32 v[60:61], v[62:63], v[64:65] op_sel_hi:[1,0]
	v_cvt_pk_bf16_f32 v56, v56, v57
	v_mul_f32_e32 v62, 0xbfb8aa3b, v60
	v_mul_f32_e32 v63, 0xbfb8aa3b, v61
	v_exp_f32_e32 v62, v62
	v_exp_f32_e32 v63, v63
	v_pk_mul_f32 v[50:51], v[50:51], v[64:65] op_sel_hi:[1,0]
	v_add_f32_e32 v62, 1.0, v62
	v_add_f32_e32 v63, 1.0, v63
	v_rcp_f32_e32 v62, v62
	v_rcp_f32_e32 v63, v63
	s_nop 0
	v_pk_mul_f32 v[60:61], v[60:61], v[62:63]
	s_nop 0
	v_pk_mul_f32 v[58:59], v[58:59], v[60:61]
	s_nop 0
	v_cvt_pk_bf16_f32 v57, v58, v59
	v_mad_i64_i32 v[58:59], s[38:39], v76, s59, v[124:125]
	v_lshl_add_u64 v[60:61], v[58:59], 0, v[126:127]
	v_mov_b32_e32 v172, v56
	v_mov_b32_e32 v173, v57
	v_lshl_add_u64 v[176:177], v[184:185], 0, v[60:61]
	v_mul_f32_e32 v56, 0xbfb8aa3b, v52
	v_mul_f32_e32 v57, 0xbfb8aa3b, v53
	v_exp_f32_e32 v56, v56
	v_exp_f32_e32 v57, v57
	v_add_u32_e32 v60, 0x90, v142
	v_ashrrev_i32_e32 v61, 31, v60
	v_add_f32_e32 v56, 1.0, v56
	v_add_f32_e32 v57, 1.0, v57
	v_rcp_f32_e32 v56, v56
	v_rcp_f32_e32 v57, v57
	s_nop 0
	v_pk_mul_f32 v[52:53], v[52:53], v[56:57]
	s_nop 0
	v_pk_mul_f32 v[48:49], v[48:49], v[52:53]
	v_pk_mul_f32 v[52:53], v[54:55], v[64:65] op_sel_hi:[1,0]
	v_cvt_pk_bf16_f32 v48, v48, v49
	v_mul_f32_e32 v54, 0xbfb8aa3b, v52
	v_mul_f32_e32 v55, 0xbfb8aa3b, v53
	v_exp_f32_e32 v54, v54
	v_exp_f32_e32 v55, v55
	v_add_f32_e32 v54, 1.0, v54
	v_add_f32_e32 v55, 1.0, v55
	v_rcp_f32_e32 v54, v54
	v_rcp_f32_e32 v55, v55
	s_nop 0
	v_pk_mul_f32 v[52:53], v[52:53], v[54:55]
	s_nop 0
	v_pk_mul_f32 v[50:51], v[50:51], v[52:53]
	s_nop 0
	v_cvt_pk_bf16_f32 v49, v50, v51
	v_lshl_add_u64 v[50:51], v[58:59], 0, v[144:145]
	v_mov_b32_e32 v174, v48
	v_mov_b32_e32 v175, v49
	s_nop 1
	v_permlane16_swap_b32 v172, v174
	v_permlane16_swap_b32 v173, v175
	global_store_dwordx4 v[176:177], v[172:175], off
	v_lshlrev_b64 v[48:49], 6, v[60:61]
	v_lshl_add_u64 v[62:63], s[16:17], 0, v[48:49]
	global_load_dwordx4 v[48:51], v[62:63], off offset:48
	global_load_dwordx4 v[52:55], v[62:63], off offset:32
	global_load_dwordx4 v[56:59], v[62:63], off offset:16
	s_nop 0
	global_load_dwordx4 v[62:65], v[62:63], off
	s_waitcnt vmcnt(0)
	v_add_f32_e32 v52, v52, v53
	v_add_f32_e32 v54, v54, v55
	v_mov_b32_e32 v66, v63
	v_mov_b32_e32 v67, v64
	v_mov_b32_e32 v63, v65
	v_mov_b32_e32 v64, v57
	v_mov_b32_e32 v65, v58
	v_mov_b32_e32 v57, v59
	v_pk_add_f32 v[62:63], v[66:67], v[62:63]
	v_pk_add_f32 v[56:57], v[64:65], v[56:57]
	v_pk_add_f32 v[62:63], v[62:63], v[62:63] op_sel:[0,1] op_sel_hi:[1,0]
	v_pk_add_f32 v[56:57], v[56:57], v[56:57] op_sel:[0,1] op_sel_hi:[1,0]
	v_mov_b32_e32 v63, v48
	v_mov_b32_e32 v57, v49
	v_mov_b32_e32 v53, v50
	v_mov_b32_e32 v55, v51
	v_pk_add_f32 v[48:49], v[62:63], v[56:57]
	v_pk_add_f32 v[50:51], v[52:53], v[54:55]
	s_nop 0
	v_pk_add_f32 v[48:49], v[48:49], v[50:51]
	s_nop 0
	v_add_f32_e32 v48, v48, v49
	v_fmamk_f32 v48, v48, 0x3a800000, v138
	v_cmp_gt_f32_e32 vcc, s64, v48
	v_mul_f32_e32 v49, 0x4b800000, v48
	s_nop 0
	v_cndmask_b32_e32 v48, v48, v49, vcc
	v_rsq_f32_e32 v48, v48
	s_nop 0
	v_mul_f32_e32 v49, 0x45800000, v48
	v_cndmask_b32_e32 v48, v48, v49, vcc
	v_pk_mul_f32 v[44:45], v[44:45], v[48:49] op_sel_hi:[1,0]
	s_nop 0
	v_mul_f32_e32 v49, 0xbfb8aa3b, v44
	v_exp_f32_e32 v49, v49
	s_nop 0
	v_add_f32_e32 v49, 1.0, v49
	v_rcp_f32_e32 v50, v49
	v_mul_f32_e32 v49, 0xbfb8aa3b, v45
	v_exp_f32_e32 v49, v49
	s_nop 0
	v_add_f32_e32 v49, 1.0, v49
	v_rcp_f32_e32 v51, v49
	v_pk_mul_f32 v[40:41], v[40:41], v[48:49] op_sel_hi:[1,0]
	v_pk_mul_f32 v[42:43], v[42:43], v[48:49] op_sel_hi:[1,0]
	v_pk_mul_f32 v[36:37], v[36:37], v[48:49] op_sel_hi:[1,0]
	v_pk_mul_f32 v[44:45], v[44:45], v[50:51]
	v_pk_mul_f32 v[32:33], v[32:33], v[48:49] op_sel_hi:[1,0]
	v_pk_mul_f32 v[40:41], v[40:41], v[44:45]
	v_pk_mul_f32 v[44:45], v[46:47], v[48:49] op_sel_hi:[1,0]
	v_cvt_pk_bf16_f32 v40, v40, v41
	v_mul_f32_e32 v46, 0xbfb8aa3b, v44
	v_mul_f32_e32 v47, 0xbfb8aa3b, v45
	v_exp_f32_e32 v46, v46
	v_exp_f32_e32 v47, v47
	v_pk_mul_f32 v[34:35], v[34:35], v[48:49] op_sel_hi:[1,0]
	v_add_f32_e32 v46, 1.0, v46
; __device__ __forceinline__ float sigmoidf_(float x) { return __builtin_amdgcn_rcpf(1.f + __expf(-x)); }
; __device__ __forceinline__ u32x2 pack4(const f32x4& a) { u32x2 w; w.x = pk2(a[0], a[1]); w.y = pk2(a[2], a[3]); return w; }
; #define EPI_LOOP_ROWS for (int am_ = 0; am_ < 8; ++am_)
; __device__ __forceinline__ float ss_rstd(const float* ssrow) { const f32x4 a = *(const f32x4*)ssrow, b = *(const f32x4*)(ssrow + 4), c = *(const f32x4*)(ssrow + 8), d = *(const f32x4*)(ssrow + 12);
;     const float s = ((a[0] + a[1]) + (a[2] + a[3])) + ((b[0] + b[1]) + (b[2] + b[3])) + ((c[0] + c[1]) + (c[2] + c[3])) + ((d[0] + d[1]) + (d[2] + d[3])); return rsqrtf(s * (1.f / D) + 1e-6f); }
;     __device__ __forceinline__ void operator()(const f32x4 (&acc)[2][2][4][2], const pg8::Unit& u, int wr, int wc, int fr, int fq) const { asm volatile("" : "+v"(fr), "+v"(fq));
;     ...
;         EPI_LOOP_ROWS { EPI_AM const int row = u.pm * 256 + ai * 128 + wr * 64 + m * 16 + fr; const float rstd = ss_rstd(ss + (size_t)row * 16);
; #pragma unroll
;             for (int bj = 0; bj < 2; ++bj) { const int col0 = u.pn * 256 + bj * 128 + wc * 32 + 8 * fq; const f32x4 g = acc[ai][bj][m][0] * rstd, up = acc[ai][bj][m][1] * rstd; f32x4 o;
; #pragma unroll
;                 for (int j = 0; j < 4; ++j) o[j] = g[j] * sigmoidf_(g[j]) * up[j];
;                 *(u32x2*)(act + (size_t)row * FF + (col0 >> 1)) = pack4(o); } }
	v_add_f32_e32 v47, 1.0, v47
	v_rcp_f32_e32 v46, v46
	v_rcp_f32_e32 v47, v47
	s_nop 0
	v_pk_mul_f32 v[44:45], v[44:45], v[46:47]
	s_nop 0
	v_pk_mul_f32 v[42:43], v[42:43], v[44:45]
	s_nop 0
	v_cvt_pk_bf16_f32 v41, v42, v43
	v_mad_i64_i32 v[42:43], s[38:39], v60, s59, v[124:125]
	v_lshl_add_u64 v[44:45], v[42:43], 0, v[126:127]
	v_mov_b32_e32 v180, v40
	v_mov_b32_e32 v181, v41
	v_lshl_add_u64 v[178:179], v[184:185], 0, v[44:45]
	v_mul_f32_e32 v40, 0xbfb8aa3b, v36
	v_mul_f32_e32 v41, 0xbfb8aa3b, v37
	v_exp_f32_e32 v40, v40
	v_exp_f32_e32 v41, v41
	v_add_u32_e32 v44, 0xa0, v142
	v_ashrrev_i32_e32 v45, 31, v44
	v_add_f32_e32 v40, 1.0, v40
	v_add_f32_e32 v41, 1.0, v41
	v_rcp_f32_e32 v40, v40
	v_rcp_f32_e32 v41, v41
	s_nop 0
	v_pk_mul_f32 v[36:37], v[36:37], v[40:41]
	s_nop 0
	v_pk_mul_f32 v[32:33], v[32:33], v[36:37]
	v_pk_mul_f32 v[36:37], v[38:39], v[48:49] op_sel_hi:[1,0]
	v_cvt_pk_bf16_f32 v32, v32, v33
	v_mul_f32_e32 v38, 0xbfb8aa3b, v36
	v_mul_f32_e32 v39, 0xbfb8aa3b, v37
	v_exp_f32_e32 v38, v38
	v_exp_f32_e32 v39, v39
	v_add_f32_e32 v38, 1.0, v38
	v_add_f32_e32 v39, 1.0, v39
	v_rcp_f32_e32 v38, v38
	v_rcp_f32_e32 v39, v39
	s_nop 0
	v_pk_mul_f32 v[36:37], v[36:37], v[38:39]
	s_nop 0
	v_pk_mul_f32 v[34:35], v[34:35], v[36:37]
	s_nop 0
	v_cvt_pk_bf16_f32 v33, v34, v35
	v_lshl_add_u64 v[34:35], v[42:43], 0, v[144:145]
	v_mov_b32_e32 v182, v32
	v_mov_b32_e32 v183, v33
	s_nop 1
	v_permlane16_swap_b32 v180, v182
	v_permlane16_swap_b32 v181, v183
	global_store_dwordx4 v[178:179], v[180:183], off
	v_lshlrev_b64 v[32:33], 6, v[44:45]
	v_lshl_add_u64 v[46:47], s[16:17], 0, v[32:33]
	global_load_dwordx4 v[32:35], v[46:47], off offset:48
	global_load_dwordx4 v[36:39], v[46:47], off offset:32
	global_load_dwordx4 v[40:43], v[46:47], off offset:16
	s_nop 0
	global_load_dwordx4 v[46:49], v[46:47], off
	s_waitcnt vmcnt(0)
	v_add_f32_e32 v36, v36, v37
	v_add_f32_e32 v38, v38, v39
	v_mov_b32_e32 v50, v47
	v_mov_b32_e32 v51, v48
	v_mov_b32_e32 v47, v49
	v_mov_b32_e32 v48, v41
	v_mov_b32_e32 v49, v42
	v_mov_b32_e32 v41, v43
	v_pk_add_f32 v[46:47], v[50:51], v[46:47]
	v_pk_add_f32 v[40:41], v[48:49], v[40:41]
	v_pk_add_f32 v[46:47], v[46:47], v[46:47] op_sel:[0,1] op_sel_hi:[1,0]
	v_pk_add_f32 v[40:41], v[40:41], v[40:41] op_sel:[0,1] op_sel_hi:[1,0]
	v_mov_b32_e32 v47, v32
	v_mov_b32_e32 v41, v33
	v_mov_b32_e32 v37, v34
	v_mov_b32_e32 v39, v35
	v_pk_add_f32 v[32:33], v[46:47], v[40:41]
	v_pk_add_f32 v[34:35], v[36:37], v[38:39]
	s_nop 0
	v_pk_add_f32 v[32:33], v[32:33], v[34:35]
	s_nop 0
	v_add_f32_e32 v32, v32, v33
	v_fmamk_f32 v32, v32, 0x3a800000, v138
	v_cmp_gt_f32_e32 vcc, s64, v32
	v_mul_f32_e32 v33, 0x4b800000, v32
	s_nop 0
	v_cndmask_b32_e32 v32, v32, v33, vcc
	v_rsq_f32_e32 v32, v32
	s_nop 0
	v_mul_f32_e32 v33, 0x45800000, v32
	v_cndmask_b32_e32 v32, v32, v33, vcc
	v_pk_mul_f32 v[28:29], v[28:29], v[32:33] op_sel_hi:[1,0]
	s_nop 0
	v_mul_f32_e32 v33, 0xbfb8aa3b, v28
	v_exp_f32_e32 v33, v33
	s_nop 0
	v_add_f32_e32 v33, 1.0, v33
	v_rcp_f32_e32 v34, v33
	v_mul_f32_e32 v33, 0xbfb8aa3b, v29
	v_exp_f32_e32 v33, v33
	s_nop 0
	v_add_f32_e32 v33, 1.0, v33
	v_rcp_f32_e32 v35, v33
	v_pk_mul_f32 v[24:25], v[24:25], v[32:33] op_sel_hi:[1,0]
	v_pk_mul_f32 v[26:27], v[26:27], v[32:33] op_sel_hi:[1,0]
	v_pk_mul_f32 v[20:21], v[20:21], v[32:33] op_sel_hi:[1,0]
	v_pk_mul_f32 v[28:29], v[28:29], v[34:35]
	v_pk_mul_f32 v[16:17], v[16:17], v[32:33] op_sel_hi:[1,0]
	v_pk_mul_f32 v[24:25], v[24:25], v[28:29]
	v_pk_mul_f32 v[28:29], v[30:31], v[32:33] op_sel_hi:[1,0]
	v_cvt_pk_bf16_f32 v24, v24, v25
	v_mul_f32_e32 v30, 0xbfb8aa3b, v28
	v_mul_f32_e32 v31, 0xbfb8aa3b, v29
	v_exp_f32_e32 v30, v30
	v_exp_f32_e32 v31, v31
	v_pk_mul_f32 v[18:19], v[18:19], v[32:33] op_sel_hi:[1,0]
	v_add_f32_e32 v30, 1.0, v30
	v_add_f32_e32 v31, 1.0, v31
	v_rcp_f32_e32 v30, v30
	v_rcp_f32_e32 v31, v31
	s_nop 0
	v_pk_mul_f32 v[28:29], v[28:29], v[30:31]
	s_nop 0
	v_pk_mul_f32 v[26:27], v[26:27], v[28:29]
	s_nop 0
	v_cvt_pk_bf16_f32 v25, v26, v27
	v_mad_i64_i32 v[26:27], s[38:39], v44, s59, v[124:125]
	v_lshl_add_u64 v[28:29], v[26:27], 0, v[126:127]
	v_mov_b32_e32 v172, v24
	v_mov_b32_e32 v173, v25
	v_lshl_add_u64 v[176:177], v[184:185], 0, v[28:29]
	v_mul_f32_e32 v24, 0xbfb8aa3b, v20
	v_mul_f32_e32 v25, 0xbfb8aa3b, v21
	v_exp_f32_e32 v24, v24
	v_exp_f32_e32 v25, v25
	v_add_u32_e32 v28, 0xb0, v142
	v_ashrrev_i32_e32 v29, 31, v28
	v_add_f32_e32 v24, 1.0, v24
	v_add_f32_e32 v25, 1.0, v25
	v_rcp_f32_e32 v24, v24
	v_rcp_f32_e32 v25, v25
	s_nop 0
	v_pk_mul_f32 v[20:21], v[20:21], v[24:25]
	s_nop 0
	v_pk_mul_f32 v[16:17], v[16:17], v[20:21]
	v_pk_mul_f32 v[20:21], v[22:23], v[32:33] op_sel_hi:[1,0]
	v_cvt_pk_bf16_f32 v16, v16, v17
	v_mul_f32_e32 v22, 0xbfb8aa3b, v20
	v_mul_f32_e32 v23, 0xbfb8aa3b, v21
	v_exp_f32_e32 v22, v22
	v_exp_f32_e32 v23, v23
	v_add_f32_e32 v22, 1.0, v22
	v_add_f32_e32 v23, 1.0, v23
	v_rcp_f32_e32 v22, v22
	v_rcp_f32_e32 v23, v23
	s_nop 0
	v_pk_mul_f32 v[20:21], v[20:21], v[22:23]
	s_nop 0
	v_pk_mul_f32 v[18:19], v[18:19], v[20:21]
	s_nop 0
	v_cvt_pk_bf16_f32 v17, v18, v19
	v_lshl_add_u64 v[18:19], v[26:27], 0, v[144:145]
	v_mov_b32_e32 v174, v16
	v_mov_b32_e32 v175, v17
	s_nop 1
	v_permlane16_swap_b32 v172, v174
	v_permlane16_swap_b32 v173, v175
	global_store_dwordx4 v[176:177], v[172:175], off
	v_lshlrev_b64 v[16:17], 6, v[28:29]
	v_lshl_add_u64 v[30:31], s[16:17], 0, v[16:17]
	global_load_dwordx4 v[16:19], v[30:31], off offset:48
	global_load_dwordx4 v[20:23], v[30:31], off offset:32
	global_load_dwordx4 v[24:27], v[30:31], off offset:16
	s_nop 0
	global_load_dwordx4 v[30:33], v[30:31], off
	s_waitcnt vmcnt(0)
; #define PG8_BAR __builtin_amdgcn_s_barrier()
; __device__ __forceinline__ float sigmoidf_(float x) { return __builtin_amdgcn_rcpf(1.f + __expf(-x)); }
; __device__ __forceinline__ u32x2 pack4(const f32x4& a) { u32x2 w; w.x = pk2(a[0], a[1]); w.y = pk2(a[2], a[3]); return w; }
; #define EPI_LOOP_ROWS for (int am_ = 0; am_ < 8; ++am_)
; template <class Epi, class Sched, bool ALIGN_EPI = false, bool SP2 = false>
; __device__ __forceinline__ void gemm_phase(PG8_LAS unsigned char* lds, const Gemm g, const Sched& S, const Epi& E, int tid_in) {
;     ...
;         if (!has_next) break;
; #pragma unroll
;         for (int a = 0; a < 2; ++a)
; #pragma unroll
;             for (int b = 0; b < 2; ++b)
; #pragma unroll
;                 for (int m = 0; m < 4; ++m)
; #pragma unroll
;                     for (int n = 0; n < 2; ++n) acc[a][b][m][n] = (f32x4){0.f, 0.f, 0.f, 0.f};
;         cur = nxt; cA = nA; cB = nB; ++ui;
;         if constexpr (ALIGN_EPI) { if (wr == 1) PG8_BAR; }
;     }
;     __device__ __forceinline__ void operator()(const f32x4 (&acc)[2][2][4][2], const pg8::Unit& u, int wr, int wc, int fr, int fq) const { asm volatile("" : "+v"(fr), "+v"(fq));
;     ...
;         EPI_LOOP_ROWS { EPI_AM const int row = u.pm * 256 + ai * 128 + wr * 64 + m * 16 + fr; const float rstd = ss_rstd(ss + (size_t)row * 16);
; #pragma unroll
;             for (int bj = 0; bj < 2; ++bj) { const int col0 = u.pn * 256 + bj * 128 + wc * 32 + 8 * fq; const f32x4 g = acc[ai][bj][m][0] * rstd, up = acc[ai][bj][m][1] * rstd; f32x4 o;
; #pragma unroll
;                 for (int j = 0; j < 4; ++j) o[j] = g[j] * sigmoidf_(g[j]) * up[j];
;                 *(u32x2*)(act + (size_t)row * FF + (col0 >> 1)) = pack4(o); } }
	v_add_f32_e32 v20, v20, v21
	v_add_f32_e32 v22, v22, v23
	v_mov_b32_e32 v34, v31
	v_mov_b32_e32 v35, v32
	v_mov_b32_e32 v31, v33
	v_mov_b32_e32 v32, v25
	v_mov_b32_e32 v33, v26
	v_mov_b32_e32 v25, v27
	v_pk_add_f32 v[30:31], v[34:35], v[30:31]
	v_pk_add_f32 v[24:25], v[32:33], v[24:25]
	v_pk_add_f32 v[30:31], v[30:31], v[30:31] op_sel:[0,1] op_sel_hi:[1,0]
	v_pk_add_f32 v[24:25], v[24:25], v[24:25] op_sel:[0,1] op_sel_hi:[1,0]
	v_mov_b32_e32 v31, v16
	v_mov_b32_e32 v25, v17
	v_mov_b32_e32 v21, v18
	v_mov_b32_e32 v23, v19
	v_pk_add_f32 v[16:17], v[30:31], v[24:25]
	v_pk_add_f32 v[18:19], v[20:21], v[22:23]
	s_nop 0
	v_pk_add_f32 v[16:17], v[16:17], v[18:19]
	s_nop 0
	v_add_f32_e32 v16, v16, v17
	v_fmamk_f32 v16, v16, 0x3a800000, v138
	v_cmp_gt_f32_e32 vcc, s64, v16
	v_mul_f32_e32 v17, 0x4b800000, v16
	s_nop 0
	v_cndmask_b32_e32 v16, v16, v17, vcc
	v_rsq_f32_e32 v16, v16
	s_nop 0
	v_mul_f32_e32 v17, 0x45800000, v16
	v_cndmask_b32_e32 v16, v16, v17, vcc
	v_pk_mul_f32 v[12:13], v[12:13], v[16:17] op_sel_hi:[1,0]
	s_and_b64 vcc, exec, s[2:3]
	v_mul_f32_e32 v17, 0xbfb8aa3b, v12
	v_exp_f32_e32 v17, v17
	s_nop 0
	v_add_f32_e32 v17, 1.0, v17
	v_rcp_f32_e32 v18, v17
	v_mul_f32_e32 v17, 0xbfb8aa3b, v13
	v_exp_f32_e32 v17, v17
	s_nop 0
	v_add_f32_e32 v17, 1.0, v17
	v_rcp_f32_e32 v19, v17
	v_pk_mul_f32 v[8:9], v[8:9], v[16:17] op_sel_hi:[1,0]
	v_pk_mul_f32 v[10:11], v[10:11], v[16:17] op_sel_hi:[1,0]
	v_pk_mul_f32 v[4:5], v[4:5], v[16:17] op_sel_hi:[1,0]
	v_pk_mul_f32 v[12:13], v[12:13], v[18:19]
	v_pk_mul_f32 v[0:1], v[0:1], v[16:17] op_sel_hi:[1,0]
	v_pk_mul_f32 v[8:9], v[8:9], v[12:13]
	v_pk_mul_f32 v[12:13], v[14:15], v[16:17] op_sel_hi:[1,0]
	v_cvt_pk_bf16_f32 v8, v8, v9
	v_mul_f32_e32 v14, 0xbfb8aa3b, v12
	v_mul_f32_e32 v15, 0xbfb8aa3b, v13
	v_exp_f32_e32 v14, v14
	v_exp_f32_e32 v15, v15
	v_pk_mul_f32 v[2:3], v[2:3], v[16:17] op_sel_hi:[1,0]
	v_add_f32_e32 v14, 1.0, v14
	v_add_f32_e32 v15, 1.0, v15
	v_rcp_f32_e32 v14, v14
	v_rcp_f32_e32 v15, v15
	s_nop 0
	v_pk_mul_f32 v[12:13], v[12:13], v[14:15]
	s_nop 0
	v_pk_mul_f32 v[10:11], v[10:11], v[12:13]
	s_nop 0
	v_cvt_pk_bf16_f32 v9, v10, v11
	v_mad_i64_i32 v[10:11], s[38:39], v28, s59, v[124:125]
	v_lshl_add_u64 v[12:13], v[10:11], 0, v[126:127]
	v_mov_b32_e32 v180, v8
	v_mov_b32_e32 v181, v9
	v_lshl_add_u64 v[178:179], v[184:185], 0, v[12:13]
	v_mul_f32_e32 v8, 0xbfb8aa3b, v4
	v_mul_f32_e32 v9, 0xbfb8aa3b, v5
	v_exp_f32_e32 v8, v8
	v_exp_f32_e32 v9, v9
	s_mov_b64 s[38:39], -1
	v_add_f32_e32 v8, 1.0, v8
	v_add_f32_e32 v9, 1.0, v9
	v_rcp_f32_e32 v8, v8
	v_rcp_f32_e32 v9, v9
	s_nop 0
	v_pk_mul_f32 v[4:5], v[4:5], v[8:9]
	s_nop 0
	v_pk_mul_f32 v[0:1], v[0:1], v[4:5]
	v_pk_mul_f32 v[4:5], v[6:7], v[16:17] op_sel_hi:[1,0]
	v_cvt_pk_bf16_f32 v0, v0, v1
	v_mul_f32_e32 v6, 0xbfb8aa3b, v4
	v_mul_f32_e32 v7, 0xbfb8aa3b, v5
	v_exp_f32_e32 v6, v6
	v_exp_f32_e32 v7, v7
	v_add_f32_e32 v6, 1.0, v6
	v_add_f32_e32 v7, 1.0, v7
	v_rcp_f32_e32 v6, v6
	v_rcp_f32_e32 v7, v7
	s_nop 0
	v_pk_mul_f32 v[4:5], v[4:5], v[6:7]
	s_nop 0
	v_pk_mul_f32 v[2:3], v[2:3], v[4:5]
	s_nop 0
	v_cvt_pk_bf16_f32 v1, v2, v3
	v_lshl_add_u64 v[2:3], v[10:11], 0, v[144:145]
	v_mov_b32_e32 v182, v0
	v_mov_b32_e32 v183, v1
	s_nop 1
	v_permlane16_swap_b32 v180, v182
	v_permlane16_swap_b32 v181, v183
	global_store_dwordx4 v[178:179], v[180:183], off
	s_cbranch_vccnz .LBB0_179
	s_andn2_b64 vcc, exec, s[14:15]
	s_cbranch_vccnz .LBB0_178
	s_barrier
	s_branch .LBB0_178
